# v22 plus the xor-32 cross-half shuffles of the attention softmax (row max, row sum) done with v_permlane32_swap instead of ds_bpermute through LDS
# speedup vs baseline: 1.0238x; 1.0238x over previous
.LBB0_1245:
	v_add_u32_e32 v36, v127, v129
	ds_read_b128 v[32:35], v36
	ds_read_b128 v[108:111], v36 offset:32
	ds_read_b128 v[112:115], v36 offset:64
	ds_read_b128 v[116:119], v36 offset:96
	v_add_u32_e32 v107, 27, v104
	s_waitcnt lgkmcnt(3)
	v_mfma_f32_32x32x16_bf16 v[32:47], v[32:35], v[48:51], 0
	v_cmp_lt_i32_e32 vcc, -1, v103
	v_cmp_le_u32_e64 s[8:9], v107, v100
	s_and_b64 vcc, vcc, s[8:9]
	v_add_u32_e32 v107, 26, v104
	v_cmp_le_u32_e64 s[8:9], v107, v100
	v_add_u32_e32 v102, s18, v102
	s_waitcnt lgkmcnt(2)
	v_mfma_f32_32x32x16_bf16 v[32:47], v[108:111], v[52:55], v[32:47]
	v_add_u32_e32 v108, 25, v104
	s_waitcnt lgkmcnt(1)
	v_mfma_f32_32x32x16_bf16 v[32:47], v[112:115], v[56:59], v[32:47]
	s_waitcnt lgkmcnt(0)
	v_mfma_f32_32x32x16_bf16 v[32:47], v[116:119], v[60:63], v[32:47]
	s_nop 11
	v_cndmask_b32_e32 v32, v173, v32, vcc
	v_cmp_lt_i32_e32 vcc, -2, v103
	s_and_b64 vcc, vcc, s[8:9]
	v_cmp_le_u32_e64 s[8:9], v108, v100
	v_cndmask_b32_e32 v33, v173, v33, vcc
	v_cmp_lt_i32_e32 vcc, -3, v103
	s_and_b64 vcc, vcc, s[8:9]
	v_add_u32_e32 v108, 24, v104
	v_cndmask_b32_e32 v34, v173, v34, vcc
	v_cmp_lt_i32_e32 vcc, -4, v103
	v_cmp_le_u32_e64 s[8:9], v108, v100
	s_and_b64 vcc, vcc, s[8:9]
	v_add_u32_e32 v108, 19, v104
	v_cndmask_b32_e32 v35, v173, v35, vcc
	v_cmp_lt_i32_e32 vcc, -9, v103
	v_cmp_le_u32_e64 s[8:9], v108, v100
	s_and_b64 vcc, vcc, s[8:9]
	v_add_u32_e32 v108, 18, v104
	v_cndmask_b32_e32 v36, v173, v36, vcc
	v_cmp_lt_i32_e32 vcc, -10, v103
	v_cmp_le_u32_e64 s[8:9], v108, v100
	s_and_b64 vcc, vcc, s[8:9]
	v_add_u32_e32 v108, 17, v104
	v_cndmask_b32_e32 v37, v173, v37, vcc
	v_cmp_lt_i32_e32 vcc, -11, v103
	v_cmp_le_u32_e64 s[8:9], v108, v100
	s_and_b64 vcc, vcc, s[8:9]
	v_add_u32_e32 v108, 16, v104
	v_cndmask_b32_e32 v38, v173, v38, vcc
	v_cmp_lt_i32_e32 vcc, -12, v103
	v_cmp_le_u32_e64 s[8:9], v108, v100
	s_and_b64 vcc, vcc, s[8:9]
	v_add_u32_e32 v108, 11, v104
	s_movk_i32 s8, 0xffef
	v_cndmask_b32_e32 v39, v173, v39, vcc
	v_cmp_lt_i32_e32 vcc, s8, v103
	v_cmp_le_u32_e64 s[8:9], v108, v100
	s_and_b64 vcc, vcc, s[8:9]
	v_max3_f32 v107, v32, s90, v33
	v_cndmask_b32_e32 v108, v173, v40, vcc
	v_add_u32_e32 v40, 10, v104
	s_movk_i32 s8, 0xffee
	v_max3_f32 v107, v107, v34, v35
	v_cmp_lt_i32_e32 vcc, s8, v103
	v_cmp_le_u32_e64 s[8:9], v40, v100
	v_max3_f32 v107, v107, v36, v37
	s_and_b64 vcc, vcc, s[8:9]
	v_max3_f32 v107, v107, v38, v39
	v_cndmask_b32_e32 v41, v173, v41, vcc
	v_max3_f32 v40, v107, v108, v41
	v_add_u32_e32 v107, 9, v104
	s_movk_i32 s8, 0xffed
	v_cmp_lt_i32_e32 vcc, s8, v103
	v_cmp_le_u32_e64 s[8:9], v107, v100
	s_and_b64 vcc, vcc, s[8:9]
	v_add_u32_e32 v107, 8, v104
	s_movk_i32 s8, 0xffec
	v_cndmask_b32_e32 v42, v173, v42, vcc
	v_cmp_lt_i32_e32 vcc, s8, v103
	v_cmp_le_u32_e64 s[8:9], v107, v100
	s_and_b64 vcc, vcc, s[8:9]
	v_add_u32_e32 v107, 3, v104
	s_movk_i32 s8, 0xffe7
	v_cndmask_b32_e32 v43, v173, v43, vcc
	v_cmp_lt_i32_e32 vcc, s8, v103
	v_cmp_le_u32_e64 s[8:9], v107, v100
	s_and_b64 vcc, vcc, s[8:9]
	v_add_u32_e32 v107, 2, v104
	s_movk_i32 s8, 0xffe6
	v_cndmask_b32_e32 v44, v173, v44, vcc
	v_cmp_lt_i32_e32 vcc, s8, v103
	v_cmp_le_u32_e64 s[8:9], v107, v100
	s_and_b64 vcc, vcc, s[8:9]
	v_add_u32_e32 v107, 1, v104
	s_movk_i32 s8, 0xffe5
	v_cndmask_b32_e32 v45, v173, v45, vcc
	v_cmp_lt_i32_e32 vcc, s8, v103
	v_cmp_le_u32_e64 s[8:9], v107, v100
	s_and_b64 vcc, vcc, s[8:9]
	s_movk_i32 s8, 0xffe4
	v_cndmask_b32_e32 v46, v173, v46, vcc
	v_cmp_lt_i32_e32 vcc, s8, v103
	v_cmp_le_u32_e64 s[8:9], v104, v100
	v_max3_f32 v40, v40, v42, v43
	s_and_b64 vcc, vcc, s[8:9]
	v_max3_f32 v40, v40, v44, v45
	v_cndmask_b32_e32 v47, v173, v47, vcc
	v_max3_f32 v40, v40, v46, v47
	v_mov_b32_e32 v107, v40
	s_nop 1
	v_permlane32_swap_b32_e32 v107, v40
	v_subrev_u32_e32 v104, 32, v104
	v_add_u32_e32 v103, 32, v103
	s_andn2_b64 vcc, exec, s[80:81]
	s_waitcnt lgkmcnt(0)
	v_max3_f32 v40, v106, v40, v107
	v_sub_f32_e32 v32, v32, v40
	v_exp_f32_e32 v32, v32
	v_sub_f32_e32 v33, v33, v40
	v_exp_f32_e32 v33, v33
	v_sub_f32_e32 v34, v34, v40
	v_exp_f32_e32 v34, v34
	v_sub_f32_e32 v35, v35, v40
	v_exp_f32_e32 v35, v35
	v_sub_f32_e32 v36, v36, v40
	v_add_f32_e32 v107, 0, v32
	v_exp_f32_e32 v109, v36
	v_add_f32_e32 v107, v33, v107
	v_add_f32_e32 v107, v34, v107
	v_add_f32_e32 v107, v35, v107
	v_sub_f32_e32 v37, v37, v40
	v_add_f32_e32 v36, v109, v107
	v_exp_f32_e32 v107, v37
	v_sub_f32_e32 v37, v38, v40
	v_exp_f32_e32 v110, v37
	v_sub_f32_e32 v37, v39, v40
	v_exp_f32_e32 v39, v37
	v_sub_f32_e32 v37, v108, v40
	v_exp_f32_e32 v108, v37
	v_sub_f32_e32 v37, v41, v40
	v_add_f32_e32 v36, v107, v36
	v_exp_f32_e32 v111, v37
	v_sub_f32_e32 v37, v42, v40
	v_add_f32_e32 v36, v110, v36
	v_exp_f32_e32 v42, v37
	v_sub_f32_e32 v37, v43, v40
	v_add_f32_e32 v36, v39, v36
	v_exp_f32_e32 v43, v37
	v_sub_f32_e32 v37, v44, v40
	v_add_f32_e32 v36, v108, v36
	v_exp_f32_e32 v44, v37
	v_sub_f32_e32 v37, v45, v40
	v_add_f32_e32 v36, v111, v36
	v_exp_f32_e32 v45, v37
	v_sub_f32_e32 v37, v46, v40
	v_add_f32_e32 v36, v42, v36
	v_exp_f32_e32 v112, v37
	v_sub_f32_e32 v37, v47, v40
	v_add_f32_e32 v36, v43, v36
	v_exp_f32_e32 v47, v37
	v_add_f32_e32 v36, v44, v36
	v_add_f32_e32 v36, v45, v36
	v_add_f32_e32 v36, v112, v36
	v_add_f32_e32 v36, v47, v36
	v_mov_b32_e32 v37, v36
	s_nop 1
	v_permlane32_swap_b32_e32 v37, v36
	v_sub_f32_e32 v106, v106, v40
	v_exp_f32_e32 v46, v106
	v_cvt_pk_bf16_f32 v38, v109, v107
	v_cvt_pk_bf16_f32 v39, v110, v39
	s_waitcnt lgkmcnt(0)
	v_add_f32_e32 v41, v36, v37
	v_cvt_pk_bf16_f32 v36, v32, v33
	v_cvt_pk_bf16_f32 v37, v34, v35
	v_cvt_pk_bf16_f32 v32, v108, v111
	v_cvt_pk_bf16_f32 v33, v42, v43
	v_cvt_pk_bf16_f32 v34, v44, v45
	v_cvt_pk_bf16_f32 v35, v112, v47
	ds_read_b64_tr_b16 v[42:43], v171 offset:4608
	ds_read_b64_tr_b16 v[44:45], v171 offset:5760
	ds_read_b64_tr_b16 v[106:107], v171 offset:6912
	ds_read_b64_tr_b16 v[108:109], v171 offset:8064
	ds_read_b64_tr_b16 v[110:111], v171 offset:4672
	ds_read_b64_tr_b16 v[112:113], v171 offset:5824
	ds_read_b64_tr_b16 v[114:115], v171 offset:6976
	ds_read_b64_tr_b16 v[116:117], v171 offset:8128
	v_pk_mul_f32 v[14:15], v[14:15], v[46:47] op_sel_hi:[1,0]
	v_pk_mul_f32 v[12:13], v[12:13], v[46:47] op_sel_hi:[1,0]
	v_pk_mul_f32 v[10:11], v[10:11], v[46:47] op_sel_hi:[1,0]
	v_pk_mul_f32 v[8:9], v[8:9], v[46:47] op_sel_hi:[1,0]
	v_pk_mul_f32 v[6:7], v[6:7], v[46:47] op_sel_hi:[1,0]
	v_pk_mul_f32 v[4:5], v[4:5], v[46:47] op_sel_hi:[1,0]
	v_pk_mul_f32 v[2:3], v[2:3], v[46:47] op_sel_hi:[1,0]
	v_pk_mul_f32 v[0:1], v[0:1], v[46:47] op_sel_hi:[1,0]
	v_pk_mul_f32 v[30:31], v[30:31], v[46:47] op_sel_hi:[1,0]
	v_pk_mul_f32 v[28:29], v[28:29], v[46:47] op_sel_hi:[1,0]
	v_pk_mul_f32 v[26:27], v[26:27], v[46:47] op_sel_hi:[1,0]
	v_pk_mul_f32 v[24:25], v[24:25], v[46:47] op_sel_hi:[1,0]
	v_pk_mul_f32 v[22:23], v[22:23], v[46:47] op_sel_hi:[1,0]
	v_pk_mul_f32 v[20:21], v[20:21], v[46:47] op_sel_hi:[1,0]
	v_pk_mul_f32 v[18:19], v[18:19], v[46:47] op_sel_hi:[1,0]
	v_pk_mul_f32 v[16:17], v[16:17], v[46:47] op_sel_hi:[1,0]
	s_waitcnt lgkmcnt(6)
	v_mfma_f32_32x32x16_bf16 v[0:15], v[42:45], v[36:39], v[0:15]
	v_fmac_f32_e32 v41, v105, v46
	s_waitcnt lgkmcnt(2)
	v_mfma_f32_32x32x16_bf16 v[16:31], v[110:113], v[36:39], v[16:31]
	v_mfma_f32_32x32x16_bf16 v[0:15], v[106:109], v[32:35], v[0:15]
	s_waitcnt lgkmcnt(0)
	v_mfma_f32_32x32x16_bf16 v[16:31], v[114:117], v[32:35], v[16:31]
	s_cbranch_vccz .LBB0_1247
	v_mov_b32_e32 v106, v40
	v_mov_b32_e32 v105, v41
	s_branch .LBB0_1243

.LBB0_1326:
	v_subrev_u32_e32 v32, 28, v182
	v_min_i32_e32 v32, s53, v32
	v_mad_u32_u24 v32, v32, v177, v178
	v_add_u32_e32 v33, -8, v32
	v_cmp_lt_i32_e32 vcc, v32, v180
	v_add_u32_e32 v211, v127, v129
	ds_read_b128 v[216:219], v211 offset:64
	v_cndmask_b32_e32 v32, v33, v32, vcc
	v_mad_u32_u24 v32, v32, v141, v130
	v_mov_b32_e32 v33, 0
	v_cndmask_b32_e32 v35, v145, v149, vcc
	v_cndmask_b32_e32 v34, v144, v148, vcc
	v_lshl_add_u64 v[34:35], v[32:33], 2, v[34:35]
	global_load_dwordx4 v[112:115], v[34:35], off
	v_cndmask_b32_e32 v35, v147, v151, vcc
	v_cndmask_b32_e32 v34, v146, v150, vcc
	v_lshl_add_u64 v[32:33], v[32:33], 2, v[34:35]
	global_load_dwordx4 v[116:119], v[32:33], off
	v_subrev_u32_e32 v32, 24, v182
	v_min_i32_e32 v32, s53, v32
	v_mad_u32_u24 v32, v32, v177, v178
	v_add_u32_e32 v33, -8, v32
	v_cmp_lt_i32_e32 vcc, v32, v180
	v_min_i32_e32 v120, s53, v182
	v_mul_u32_u24_e32 v120, v120, v177
	v_cndmask_b32_e32 v32, v33, v32, vcc
	v_mad_u32_u24 v32, v32, v141, v130
	v_mov_b32_e32 v33, 0
	v_cndmask_b32_e32 v35, v145, v149, vcc
	v_cndmask_b32_e32 v34, v144, v148, vcc
	v_lshl_add_u64 v[34:35], v[32:33], 2, v[34:35]
	global_load_dwordx4 v[104:107], v[34:35], off
	v_cndmask_b32_e32 v35, v147, v151, vcc
	v_cndmask_b32_e32 v34, v146, v150, vcc
	v_lshl_add_u64 v[32:33], v[32:33], 2, v[34:35]
	global_load_dwordx4 v[108:111], v[32:33], off
	v_subrev_u32_e32 v32, 20, v182
	v_min_i32_e32 v32, s53, v32
	v_mad_u32_u24 v32, v32, v177, v178
	v_add_u32_e32 v33, -8, v32
	v_cmp_lt_i32_e32 vcc, v32, v180
	v_add_u32_e32 v120, v120, v178
	v_add_u32_e32 v209, -8, v120
	v_cndmask_b32_e32 v32, v33, v32, vcc
	v_mad_u32_u24 v32, v32, v141, v130
	v_mov_b32_e32 v33, 0
	v_cndmask_b32_e32 v35, v145, v149, vcc
	v_cndmask_b32_e32 v34, v144, v148, vcc
	v_lshl_add_u64 v[34:35], v[32:33], 2, v[34:35]
	global_load_dwordx4 v[96:99], v[34:35], off
	v_cndmask_b32_e32 v35, v147, v151, vcc
	v_cndmask_b32_e32 v34, v146, v150, vcc
	v_lshl_add_u64 v[32:33], v[32:33], 2, v[34:35]
	global_load_dwordx4 v[100:103], v[32:33], off
	v_add_u32_e32 v32, -16, v182
	v_min_i32_e32 v32, s53, v32
	v_mad_u32_u24 v32, v32, v177, v178
	v_add_u32_e32 v33, -8, v32
	v_cmp_lt_i32_e32 vcc, v32, v180
	v_add_u32_e32 v184, v184, v186
	v_add_u32_e32 v201, v201, v185
	v_cndmask_b32_e32 v32, v33, v32, vcc
	v_mad_u32_u24 v32, v32, v141, v130
	v_mov_b32_e32 v33, 0
	v_cndmask_b32_e32 v35, v145, v149, vcc
	v_cndmask_b32_e32 v34, v144, v148, vcc
	v_lshl_add_u64 v[34:35], v[32:33], 2, v[34:35]
	global_load_dwordx4 v[88:91], v[34:35], off
	v_cndmask_b32_e32 v35, v147, v151, vcc
	v_cndmask_b32_e32 v34, v146, v150, vcc
	v_lshl_add_u64 v[32:33], v[32:33], 2, v[34:35]
	global_load_dwordx4 v[92:95], v[32:33], off
	v_add_u32_e32 v32, -12, v182
	v_min_i32_e32 v32, s53, v32
	v_mad_u32_u24 v32, v32, v177, v178
	v_add_u32_e32 v33, -8, v32
	v_cmp_lt_i32_e32 vcc, v32, v180
	ds_read_b128 v[212:215], v211 offset:32
	v_add_u32_e32 v188, v188, v186
	v_cndmask_b32_e32 v32, v33, v32, vcc
	v_mad_u32_u24 v32, v32, v141, v130
	v_mov_b32_e32 v33, 0
	v_cndmask_b32_e32 v35, v145, v149, vcc
	v_cndmask_b32_e32 v34, v144, v148, vcc
	v_lshl_add_u64 v[34:35], v[32:33], 2, v[34:35]
	global_load_dwordx4 v[80:83], v[34:35], off
	v_cndmask_b32_e32 v35, v147, v151, vcc
	v_cndmask_b32_e32 v34, v146, v150, vcc
	v_lshl_add_u64 v[32:33], v[32:33], 2, v[34:35]
	global_load_dwordx4 v[84:87], v[32:33], off
	v_add_u32_e32 v32, -8, v182
	v_min_i32_e32 v32, s53, v32
	v_mad_u32_u24 v32, v32, v177, v178
	v_add_u32_e32 v33, -8, v32
	v_cmp_lt_i32_e32 vcc, v32, v180
	v_add_u32_e32 v190, v190, v186
	v_add_u32_e32 v192, v192, v186
	v_cndmask_b32_e32 v32, v33, v32, vcc
	v_mad_u32_u24 v32, v32, v141, v130
	v_mov_b32_e32 v33, 0
	v_cndmask_b32_e32 v35, v145, v149, vcc
	v_cndmask_b32_e32 v34, v144, v148, vcc
	v_lshl_add_u64 v[34:35], v[32:33], 2, v[34:35]
	global_load_dwordx4 v[64:67], v[34:35], off
	v_cndmask_b32_e32 v35, v147, v151, vcc
	v_cndmask_b32_e32 v34, v146, v150, vcc
	v_lshl_add_u64 v[32:33], v[32:33], 2, v[34:35]
	global_load_dwordx4 v[68:71], v[32:33], off
	v_add_u32_e32 v32, -4, v182
	v_min_i32_e32 v32, s53, v32
	v_mul_u32_u24_e32 v32, v32, v177
	v_add_u32_e32 v32, v32, v178
	v_add_u32_e32 v33, -8, v32
	v_cmp_lt_i32_e32 vcc, v32, v180
	v_add_u32_e32 v182, 32, v182
	v_add_u32_e32 v194, v194, v186
	v_cndmask_b32_e32 v32, v33, v32, vcc
	v_mul_u32_u24_e32 v32, v32, v141
	v_or_b32_e32 v36, v32, v130
	v_mov_b32_e32 v37, 0
	ds_read_b128 v[32:35], v211
	v_cndmask_b32_e32 v39, v145, v149, vcc
	v_cndmask_b32_e32 v38, v144, v148, vcc
	v_lshlrev_b64 v[76:77], 2, v[36:37]
	v_lshl_add_u64 v[36:37], v[38:39], 0, v[76:77]
	global_load_dwordx4 v[72:75], v[36:37], off
	s_waitcnt lgkmcnt(0)
	v_mfma_f32_32x32x16_bf16 v[32:47], v[32:35], v[56:59], 0
	v_cndmask_b32_e32 v79, v147, v151, vcc
	v_cndmask_b32_e32 v78, v146, v150, vcc
	v_cmp_lt_i32_e32 vcc, v120, v180
	v_lshl_add_u64 v[76:77], v[78:79], 0, v[76:77]
	global_load_dwordx4 v[76:79], v[76:77], off
	v_cndmask_b32_e32 v120, v209, v120, vcc
	v_mul_u32_u24_e32 v220, v120, v141
	v_mfma_f32_32x32x16_bf16 v[32:47], v[212:215], v[60:63], v[32:47]
	ds_read_b128 v[212:215], v211 offset:96
	v_add_u32_e32 v196, v196, v186
	v_add_u32_e32 v198, v198, v186
	v_add_u32_e32 v200, v200, v186
	v_mfma_f32_32x32x16_bf16 v[32:47], v[216:219], v[52:55], v[32:47]
	v_add_u32_e32 v120, s33, v181
	v_cmp_le_u32_e64 s[16:17], v120, v135
	v_or_b32_e32 v218, v220, v130
	v_mov_b32_e32 v219, 0
	v_cndmask_b32_e32 v217, v145, v149, vcc
	s_waitcnt lgkmcnt(0)
	v_mfma_f32_32x32x16_bf16 v[32:47], v[212:215], v[48:51], v[32:47]
	v_cndmask_b32_e32 v216, v144, v148, vcc
	v_lshlrev_b64 v[218:219], 2, v[218:219]
	s_sub_i32 s33, s33, 32
	s_nop 8
	v_cndmask_b32_e64 v210, v173, v32, s[16:17]
	v_add_u32_e32 v32, -1, v120
	v_cmp_le_u32_e64 s[16:17], v32, v135
	s_nop 1
	v_cndmask_b32_e64 v212, v173, v33, s[16:17]
	v_add_u32_e32 v33, -2, v120
	v_cmp_le_u32_e64 s[16:17], v33, v135
	v_add_u32_e32 v33, -3, v120
	v_max3_f32 v32, v210, s90, v212
	v_cndmask_b32_e64 v213, v173, v34, s[16:17]
	v_cmp_le_u32_e64 s[16:17], v33, v135
	v_add_u32_e32 v33, -8, v120
	s_nop 0
	v_cndmask_b32_e64 v214, v173, v35, s[16:17]
	v_cmp_le_u32_e64 s[16:17], v33, v135
	v_add_u32_e32 v33, -9, v120
	v_max3_f32 v32, v32, v213, v214
	v_cndmask_b32_e64 v215, v173, v36, s[16:17]
	v_cmp_le_u32_e64 s[16:17], v33, v135
	v_add_u32_e32 v33, -10, v120
	v_cndmask_b32_e32 v36, v146, v150, vcc
	v_cndmask_b32_e64 v220, v173, v37, s[16:17]
	v_cmp_le_u32_e64 s[16:17], v33, v135
	v_add_u32_e32 v33, -11, v120
	v_max3_f32 v32, v32, v215, v220
	v_cndmask_b32_e64 v221, v173, v38, s[16:17]
	v_cmp_le_u32_e64 s[16:17], v33, v135
	v_add_u32_e32 v33, -16, v120
	v_cndmask_b32_e32 v37, v147, v151, vcc
	v_cndmask_b32_e64 v222, v173, v39, s[16:17]
	v_cmp_le_u32_e64 s[16:17], v33, v135
	v_subrev_u32_e32 v33, 17, v120
	v_max3_f32 v32, v32, v221, v222
	v_cndmask_b32_e64 v40, v173, v40, s[16:17]
	v_cmp_le_u32_e64 s[16:17], v33, v135
	v_subrev_u32_e32 v33, 18, v120
	v_lshl_add_u64 v[36:37], v[36:37], 0, v[218:219]
	v_cndmask_b32_e64 v41, v173, v41, s[16:17]
	v_cmp_le_u32_e64 s[16:17], v33, v135
	v_subrev_u32_e32 v33, 19, v120
	v_max3_f32 v32, v32, v40, v41
	v_cndmask_b32_e64 v42, v173, v42, s[16:17]
	v_cmp_le_u32_e64 s[16:17], v33, v135
	v_subrev_u32_e32 v33, 24, v120
	s_nop 0
	v_cndmask_b32_e64 v43, v173, v43, s[16:17]
	v_cmp_le_u32_e64 s[16:17], v33, v135
	v_subrev_u32_e32 v33, 25, v120
	v_max3_f32 v32, v32, v42, v43
	v_cndmask_b32_e64 v44, v173, v44, s[16:17]
	v_cmp_le_u32_e64 s[16:17], v33, v135
	v_subrev_u32_e32 v33, 26, v120
	s_nop 0
	v_cndmask_b32_e64 v45, v173, v45, s[16:17]
	v_cmp_le_u32_e64 s[16:17], v33, v135
	v_subrev_u32_e32 v33, 27, v120
	v_max3_f32 v32, v32, v44, v45
	v_cndmask_b32_e64 v46, v173, v46, s[16:17]
	v_cmp_le_u32_e64 s[16:17], v33, v135
	s_nop 1
	v_cndmask_b32_e64 v47, v173, v47, s[16:17]
	v_max3_f32 v38, v32, v46, v47
	v_mov_b32_e32 v39, v38
	s_nop 1
	v_permlane32_swap_b32_e32 v39, v38
	v_lshl_add_u64 v[32:33], v[216:217], 0, v[218:219]
	global_load_dwordx4 v[32:35], v[32:33], off
	s_add_i32 s16, s18, s33
	s_cmp_lg_u32 s16, 0
	s_waitcnt lgkmcnt(0)
	v_max3_f32 v209, v208, v38, v39
	v_sub_f32_e32 v38, v210, v209
	v_exp_f32_e32 v210, v38
	global_load_dwordx4 v[36:39], v[36:37], off
	v_sub_f32_e32 v212, v212, v209
	v_exp_f32_e32 v212, v212
	v_sub_f32_e32 v213, v213, v209
	v_exp_f32_e32 v213, v213
	v_sub_f32_e32 v214, v214, v209
	v_exp_f32_e32 v214, v214
	v_sub_f32_e32 v215, v215, v209
	v_sub_f32_e32 v120, v208, v209
	v_add_f32_e32 v208, 0, v210
	v_exp_f32_e32 v215, v215
	v_sub_f32_e32 v216, v220, v209
	v_add_f32_e32 v208, v212, v208
	v_exp_f32_e32 v216, v216
	v_sub_f32_e32 v217, v221, v209
	v_add_f32_e32 v208, v213, v208
	v_exp_f32_e32 v217, v217
	v_sub_f32_e32 v218, v222, v209
	v_add_f32_e32 v208, v214, v208
	v_exp_f32_e32 v218, v218
	v_sub_f32_e32 v40, v40, v209
	v_add_f32_e32 v208, v215, v208
	v_exp_f32_e32 v220, v40
	v_sub_f32_e32 v41, v41, v209
	v_add_f32_e32 v40, v216, v208
	v_exp_f32_e32 v208, v41
	v_sub_f32_e32 v41, v42, v209
	v_add_f32_e32 v40, v217, v40
	v_exp_f32_e32 v221, v41
	v_sub_f32_e32 v41, v43, v209
	v_add_f32_e32 v40, v218, v40
	v_exp_f32_e32 v222, v41
	v_sub_f32_e32 v41, v44, v209
	v_add_f32_e32 v40, v220, v40
	v_exp_f32_e32 v223, v41
	v_sub_f32_e32 v41, v45, v209
	v_add_f32_e32 v40, v208, v40
	v_exp_f32_e32 v224, v41
	v_sub_f32_e32 v41, v46, v209
	v_add_f32_e32 v40, v221, v40
	v_exp_f32_e32 v225, v41
	v_sub_f32_e32 v41, v47, v209
	v_add_f32_e32 v40, v222, v40
	v_exp_f32_e32 v226, v41
	v_add_f32_e32 v40, v223, v40
	v_add_f32_e32 v40, v224, v40
	v_add_f32_e32 v40, v225, v40
	v_exp_f32_e32 v120, v120
	v_add_f32_e32 v227, v226, v40
	ds_read_b64_tr_b16 v[40:41], v175 offset:4608
	ds_read_b64_tr_b16 v[42:43], v175 offset:5760
	v_cvt_pk_bf16_f32 v44, v210, v212
	v_cvt_pk_bf16_f32 v45, v213, v214
	v_cvt_pk_bf16_f32 v46, v215, v216
	v_cvt_pk_bf16_f32 v47, v217, v218
	ds_read_b64_tr_b16 v[212:213], v175 offset:6912
	ds_read_b64_tr_b16 v[214:215], v175 offset:8064
	ds_read_b64_tr_b16 v[218:219], v175 offset:5824
	ds_read_b64_tr_b16 v[216:217], v175 offset:4672
	v_pk_mul_f32 v[14:15], v[14:15], v[120:121] op_sel_hi:[1,0]
	v_pk_mul_f32 v[12:13], v[12:13], v[120:121] op_sel_hi:[1,0]
	v_pk_mul_f32 v[10:11], v[10:11], v[120:121] op_sel_hi:[1,0]
	v_pk_mul_f32 v[8:9], v[8:9], v[120:121] op_sel_hi:[1,0]
	v_pk_mul_f32 v[6:7], v[6:7], v[120:121] op_sel_hi:[1,0]
	v_pk_mul_f32 v[4:5], v[4:5], v[120:121] op_sel_hi:[1,0]
	v_pk_mul_f32 v[2:3], v[2:3], v[120:121] op_sel_hi:[1,0]
	v_pk_mul_f32 v[0:1], v[0:1], v[120:121] op_sel_hi:[1,0]
	v_pk_mul_f32 v[30:31], v[30:31], v[120:121] op_sel_hi:[1,0]
	v_pk_mul_f32 v[28:29], v[28:29], v[120:121] op_sel_hi:[1,0]
	v_pk_mul_f32 v[26:27], v[26:27], v[120:121] op_sel_hi:[1,0]
	v_pk_mul_f32 v[24:25], v[24:25], v[120:121] op_sel_hi:[1,0]
	v_pk_mul_f32 v[22:23], v[22:23], v[120:121] op_sel_hi:[1,0]
	v_pk_mul_f32 v[20:21], v[20:21], v[120:121] op_sel_hi:[1,0]
	v_pk_mul_f32 v[18:19], v[18:19], v[120:121] op_sel_hi:[1,0]
	v_pk_mul_f32 v[16:17], v[16:17], v[120:121] op_sel_hi:[1,0]
	s_waitcnt lgkmcnt(4)
	v_mfma_f32_32x32x16_bf16 v[0:15], v[40:43], v[44:47], v[0:15]
	v_cvt_pk_bf16_f32 v40, v220, v208
	v_cvt_pk_bf16_f32 v41, v221, v222
	v_cvt_pk_bf16_f32 v42, v223, v224
	ds_read_b64_tr_b16 v[222:223], v175 offset:8128
	ds_read_b64_tr_b16 v[220:221], v175 offset:6976
	v_cvt_pk_bf16_f32 v43, v225, v226
	s_waitcnt lgkmcnt(2)
	v_mfma_f32_32x32x16_bf16 v[16:31], v[216:219], v[44:47], v[16:31]
	v_mov_b32_e32 v44, v227
	s_nop 1
	v_permlane32_swap_b32_e32 v44, v227
	s_waitcnt lgkmcnt(0)
	v_add_f32_e32 v210, v227, v44
	v_fmac_f32_e32 v210, v202, v120
	v_mfma_f32_32x32x16_bf16 v[0:15], v[212:215], v[40:43], v[0:15]
	v_mfma_f32_32x32x16_bf16 v[16:31], v[220:223], v[40:43], v[16:31]
	s_cbranch_scc0 .LBB0_1328
	v_mov_b32_e32 v208, v209
	v_mov_b32_e32 v202, v210
	s_branch .LBB0_1284

.LBB0_1370:
	ds_read_b128 v[32:35], v211
	ds_read_b128 v[64:67], v211 offset:32
	s_waitcnt lgkmcnt(1)
	v_mfma_f32_32x32x16_bf16 v[32:47], v[32:35], v[56:59], 0
	s_waitcnt lgkmcnt(0)
	v_mfma_f32_32x32x16_bf16 v[32:47], v[64:67], v[60:63], v[32:47]
	ds_read_b128 v[56:59], v211 offset:64
	ds_read_b128 v[60:63], v211 offset:96
	v_add_u32_e32 v64, v148, v125
	v_sub_u32_e32 v65, v139, v64
	v_xad_u32 v64, v64, -1, v139
	v_cmp_le_u32_e32 vcc, v65, v135
	v_add_u32_e32 v66, -2, v65
	v_add_u32_e32 v67, -3, v65
	s_waitcnt lgkmcnt(1)
	v_mfma_f32_32x32x16_bf16 v[32:47], v[56:59], v[52:55], v[32:47]
	v_add_u32_e32 v52, -8, v65
	v_add_u32_e32 v53, -9, v65
	v_add_u32_e32 v54, -10, v65
	v_add_u32_e32 v55, -11, v65
	v_add_u32_e32 v56, -16, v65
	v_subrev_u32_e32 v57, 17, v65
	v_subrev_u32_e32 v58, 18, v65
	s_waitcnt lgkmcnt(0)
	v_mfma_f32_32x32x16_bf16 v[32:47], v[60:63], v[48:51], v[32:47]
	v_subrev_u32_e32 v49, 19, v65
	s_nop 10
	v_cndmask_b32_e32 v32, v173, v32, vcc
	v_cmp_le_u32_e32 vcc, v64, v135
	s_nop 1
	v_cndmask_b32_e32 v33, v173, v33, vcc
	v_cmp_le_u32_e32 vcc, v66, v135
	s_nop 1
	v_cndmask_b32_e32 v34, v173, v34, vcc
	v_cmp_le_u32_e32 vcc, v67, v135
	s_nop 1
	v_cndmask_b32_e32 v35, v173, v35, vcc
	v_cmp_le_u32_e32 vcc, v52, v135
	s_nop 1
	v_cndmask_b32_e32 v36, v173, v36, vcc
	v_cmp_le_u32_e32 vcc, v53, v135
	s_nop 1
	v_cndmask_b32_e32 v37, v173, v37, vcc
	v_cmp_le_u32_e32 vcc, v54, v135
	s_nop 1
	v_cndmask_b32_e32 v38, v173, v38, vcc
	v_cmp_le_u32_e32 vcc, v55, v135
	s_nop 1
	v_cndmask_b32_e32 v39, v173, v39, vcc
	v_cmp_le_u32_e32 vcc, v56, v135
	s_nop 1
	v_cndmask_b32_e32 v48, v173, v40, vcc
	v_cmp_le_u32_e32 vcc, v57, v135
	v_max3_f32 v40, v32, s90, v33
	v_max3_f32 v40, v40, v34, v35
	v_cndmask_b32_e32 v41, v173, v41, vcc
	v_cmp_le_u32_e32 vcc, v58, v135
	v_max3_f32 v40, v40, v36, v37
	v_max3_f32 v40, v40, v38, v39
	v_cndmask_b32_e32 v42, v173, v42, vcc
	v_cmp_le_u32_e32 vcc, v49, v135
	v_subrev_u32_e32 v49, 24, v65
	v_max3_f32 v40, v40, v48, v41
	v_cndmask_b32_e32 v43, v173, v43, vcc
	v_cmp_le_u32_e32 vcc, v49, v135
	v_subrev_u32_e32 v49, 25, v65
	v_max3_f32 v40, v40, v42, v43
	v_cndmask_b32_e32 v44, v173, v44, vcc
	v_cmp_le_u32_e32 vcc, v49, v135
	v_subrev_u32_e32 v49, 26, v65
	s_nop 0
	v_cndmask_b32_e32 v45, v173, v45, vcc
	v_cmp_le_u32_e32 vcc, v49, v135
	v_subrev_u32_e32 v49, 27, v65
	v_max3_f32 v40, v40, v44, v45
	v_cndmask_b32_e32 v46, v173, v46, vcc
	v_cmp_le_u32_e32 vcc, v49, v135
	s_nop 1
	v_cndmask_b32_e32 v47, v173, v47, vcc
	v_max3_f32 v40, v40, v46, v47
	v_mov_b32_e32 v49, v40
	s_nop 1
	v_permlane32_swap_b32_e32 v49, v40
	s_waitcnt lgkmcnt(0)
	v_max3_f32 v40, v209, v40, v49
	v_sub_f32_e32 v32, v32, v40
	v_exp_f32_e32 v49, v32
	v_sub_f32_e32 v33, v33, v40
	v_exp_f32_e32 v51, v33
	v_sub_f32_e32 v33, v34, v40
	v_exp_f32_e32 v52, v33
	v_sub_f32_e32 v33, v35, v40
	v_exp_f32_e32 v53, v33
	v_sub_f32_e32 v33, v36, v40
	v_add_f32_e32 v50, 0, v49
	v_exp_f32_e32 v55, v33
	v_sub_f32_e32 v34, v37, v40
	v_add_f32_e32 v33, v51, v50
	v_exp_f32_e32 v50, v34
	v_sub_f32_e32 v34, v38, v40
	v_add_f32_e32 v33, v52, v33
	v_exp_f32_e32 v56, v34
	v_sub_f32_e32 v34, v39, v40
	v_add_f32_e32 v33, v53, v33
	v_exp_f32_e32 v39, v34
	v_sub_f32_e32 v34, v48, v40
	v_add_f32_e32 v33, v55, v33
	v_exp_f32_e32 v57, v34
	v_sub_f32_e32 v34, v41, v40
	v_add_f32_e32 v33, v50, v33
	v_exp_f32_e32 v41, v34
	v_sub_f32_e32 v34, v42, v40
	v_add_f32_e32 v33, v56, v33
	v_exp_f32_e32 v58, v34
	v_sub_f32_e32 v34, v43, v40
	v_add_f32_e32 v33, v39, v33
	v_exp_f32_e32 v59, v34
	v_sub_f32_e32 v34, v44, v40
	v_add_f32_e32 v33, v57, v33
	v_exp_f32_e32 v60, v34
	v_sub_f32_e32 v34, v45, v40
	v_add_f32_e32 v33, v41, v33
	v_exp_f32_e32 v61, v34
	v_sub_f32_e32 v34, v46, v40
	v_add_f32_e32 v33, v58, v33
	v_exp_f32_e32 v62, v34
	v_sub_f32_e32 v34, v47, v40
	v_add_f32_e32 v33, v59, v33
	v_exp_f32_e32 v63, v34
	v_sub_f32_e32 v32, v209, v40
	v_add_f32_e32 v33, v60, v33
	v_exp_f32_e32 v54, v32
	v_add_f32_e32 v32, v61, v33
	v_add_f32_e32 v32, v62, v32
	v_add_f32_e32 v64, v63, v32
	ds_read_b64_tr_b16 v[32:33], v175 offset:4608
	ds_read_b64_tr_b16 v[34:35], v175 offset:5760
	v_cvt_pk_bf16_f32 v36, v49, v51
	ds_read_b64_tr_b16 v[42:43], v175 offset:6912
	ds_read_b64_tr_b16 v[44:45], v175 offset:8064
	ds_read_b64_tr_b16 v[48:49], v175 offset:5824
	ds_read_b64_tr_b16 v[46:47], v175 offset:4672
	v_pk_mul_f32 v[14:15], v[14:15], v[54:55] op_sel_hi:[1,0]
	v_pk_mul_f32 v[12:13], v[12:13], v[54:55] op_sel_hi:[1,0]
	v_pk_mul_f32 v[10:11], v[10:11], v[54:55] op_sel_hi:[1,0]
	v_pk_mul_f32 v[8:9], v[8:9], v[54:55] op_sel_hi:[1,0]
	v_pk_mul_f32 v[6:7], v[6:7], v[54:55] op_sel_hi:[1,0]
	v_pk_mul_f32 v[4:5], v[4:5], v[54:55] op_sel_hi:[1,0]
	v_pk_mul_f32 v[2:3], v[2:3], v[54:55] op_sel_hi:[1,0]
	v_pk_mul_f32 v[0:1], v[0:1], v[54:55] op_sel_hi:[1,0]
	v_cvt_pk_bf16_f32 v37, v52, v53
	v_cvt_pk_bf16_f32 v38, v55, v50
	v_cvt_pk_bf16_f32 v39, v56, v39
	v_pk_mul_f32 v[30:31], v[30:31], v[54:55] op_sel_hi:[1,0]
	v_pk_mul_f32 v[28:29], v[28:29], v[54:55] op_sel_hi:[1,0]
	v_pk_mul_f32 v[26:27], v[26:27], v[54:55] op_sel_hi:[1,0]
	v_pk_mul_f32 v[24:25], v[24:25], v[54:55] op_sel_hi:[1,0]
	v_pk_mul_f32 v[22:23], v[22:23], v[54:55] op_sel_hi:[1,0]
	v_pk_mul_f32 v[20:21], v[20:21], v[54:55] op_sel_hi:[1,0]
	v_pk_mul_f32 v[18:19], v[18:19], v[54:55] op_sel_hi:[1,0]
	v_pk_mul_f32 v[16:17], v[16:17], v[54:55] op_sel_hi:[1,0]
	s_waitcnt lgkmcnt(4)
	v_mfma_f32_32x32x16_bf16 v[0:15], v[32:35], v[36:39], v[0:15]
	ds_read_b64_tr_b16 v[52:53], v175 offset:8128
	ds_read_b64_tr_b16 v[50:51], v175 offset:6976
	v_cvt_pk_bf16_f32 v32, v57, v41
	v_cvt_pk_bf16_f32 v33, v58, v59
	v_cvt_pk_bf16_f32 v34, v60, v61
	v_cvt_pk_bf16_f32 v35, v62, v63
	s_waitcnt lgkmcnt(2)
	v_mfma_f32_32x32x16_bf16 v[16:31], v[46:49], v[36:39], v[16:31]
	v_mov_b32_e32 v36, v64
	s_nop 1
	v_permlane32_swap_b32_e32 v36, v64
	s_waitcnt lgkmcnt(0)
	v_add_f32_e32 v41, v64, v36
	v_fmac_f32_e32 v41, v210, v54
	v_mfma_f32_32x32x16_bf16 v[0:15], v[42:45], v[32:35], v[0:15]
	v_mfma_f32_32x32x16_bf16 v[16:31], v[50:53], v[32:35], v[16:31]
	v_cmp_ne_u32_e32 vcc, 1, v133
	s_mov_b64 s[8:9], -1
	s_cbranch_vccnz .LBB0_1229
